# attn_prep chunks spread over all 512 blocks + hand-scheduled rwkv_prep lora loops (pipelined LDS reads, packed f32 FMAs)
# speedup vs baseline: 1.0877x; 1.0037x over previous
.LBB0_672:
	s_cmpk_gt_i32 s34, 0x1ff
	s_cbranch_scc1 .Laps_after_attn
	v_readlane_b32 s0, v209, 2
	s_mul_i32 s0, s0, 0x55
	s_add_i32 s1, s0, 0x55
	s_lshr_b32 s0, s0, 3
	s_lshr_b32 s1, s1, 3
	s_sub_i32 s1, s1, s0
	s_mul_hi_u32 s2, s0, 0xcccccccd
	s_lshr_b32 s2, s2, 4
	s_mul_i32 s3, s2, 20
	s_sub_i32 s0, s0, s3
	s_add_i32 s1, s0, s1
	s_min_u32 s3, s1, 20
	s_sub_i32 s1, s1, s3
	s_lshl_b32 s0, s0, 7
	s_lshl_b32 s3, s3, 7
	s_lshl_b32 s1, s1, 7
	v_writelane_b32 v206, s0, 40
	v_writelane_b32 v206, s3, 41
	v_writelane_b32 v206, s1, 42
	s_add_i32 s34, s2, 0x200
	s_lshl_b32 s33, s2, 6
	s_branch .LBB0_673
.Laps_after_attn:
	v_readlane_b32 s0, v206, 42
	s_cmp_eq_u32 s0, 0
	s_cbranch_scc1 .LBB0_712
	s_mov_b32 s1, 0
	v_writelane_b32 v206, s1, 40
	v_writelane_b32 v206, s0, 41
	v_writelane_b32 v206, s1, 42
	s_add_i32 s34, s34, 1
	s_addk_i32 s33, 0x40

.LBB0_678:
	v_ashrrev_i32_e32 v22, 2, v0
	v_and_b32_e32 v4, 3, v0
	v_and_b32_e32 v0, 1, v0
	v_mov_b32_e32 v2, s4
	v_cmp_eq_u32_e32 vcc, 0, v0
	v_lshlrev_b32_e32 v24, 4, v4
	v_lshlrev_b32_e32 v5, 5, v4
	v_cndmask_b32_e32 v2, v22, v2, vcc
	s_lshl_b32 s2, s10, 1
	v_cmp_gt_u32_e64 s[38:39], 2, v4
	v_ashrrev_i32_e32 v3, 31, v2
	v_lshlrev_b32_e32 v0, 1, v22
	s_movk_i32 s3, 0x90
	v_mul_u32_u24_e32 v7, 0x480, v4
	v_mul_u32_u24_e32 v4, 0x8e0, v4
	v_lshlrev_b64 v[2:3], 7, v[2:3]
	v_mul_lo_u32 v6, v22, s3
	s_sub_i32 s40, s2, 18
	v_lshl_add_u32 v25, v7, 1, v0
	v_add3_u32 v72, v5, v4, v0
	s_lshl_b64 s[2:3], s[10:11], 1
	v_add_u32_e32 v0, s33, v22
	s_mov_b64 s[52:53], s[80:81]
	v_lshl_add_u64 v[28:29], s[92:93], 0, v[2:3]
	s_add_u32 s48, s2, -16
	v_mad_i64_i32 v[2:3], s[2:3], v0, s70, 0
	s_mov_b64 s[54:55], s[82:83]
	s_mov_b64 s[56:57], s[84:85]
	s_mov_b64 s[58:59], s[86:87]
	s_mov_b64 s[60:61], s[88:89]
	s_mov_b64 s[62:63], s[90:91]
	s_mov_b64 s[64:65], s[92:93]
	s_mov_b64 s[66:67], s[94:95]
	v_readlane_b32 s72, v210, 50
	v_or_b32_e32 v2, v2, v5
	v_readlane_b32 s80, v210, 58
	v_readlane_b32 s81, v210, 59
	v_readlane_b32 s82, v210, 60
	v_readlane_b32 s83, v210, 61
	v_readlane_b32 s84, v210, 62
	v_readlane_b32 s85, v210, 63
	v_readlane_b32 s86, v209, 0
	v_readlane_b32 s87, v209, 1
	v_lshl_add_u64 v[30:31], s[84:85], 0, v[2:3]
	s_mov_b64 s[94:95], s[66:67]
	v_readlane_b32 s73, v210, 51
	v_readlane_b32 s74, v210, 52
	v_readlane_b32 s75, v210, 53
	v_readlane_b32 s76, v210, 54
	v_readlane_b32 s77, v210, 55
	v_readlane_b32 s78, v210, 56
	v_readlane_b32 s79, v210, 57
	s_mov_b64 s[92:93], s[64:65]
	s_mov_b64 s[90:91], s[62:63]
	s_mov_b64 s[88:89], s[60:61]
	s_mov_b64 s[86:87], s[58:59]
	s_mov_b64 s[84:85], s[56:57]
	s_mov_b64 s[82:83], s[54:55]
	s_mov_b64 s[80:81], s[52:53]
	v_readlane_b32 s60, v209, 3
	s_mov_b32 s45, s11
	v_ashrrev_i32_e32 v23, 31, v22
	s_lshl_b32 s35, s10, 2
	v_readlane_b32 s72, v208, 43
	v_readlane_b32 s67, v209, 10
	v_lshl_add_u64 v[26:27], s[44:45], 0, v[22:23]
	s_add_i32 s41, s35, -8
	s_lshl_b64 s[46:47], s[10:11], 2
	v_readlane_b32 s2, v206, 40
	s_mov_b32 s3, 0
	v_add_u32_e32 v73, v5, v6
	s_lshr_b32 s36, s2, 7
	s_mov_b32 s37, 0
	v_readlane_b32 s73, v208, 44
	v_readlane_b32 s74, v208, 45
	v_readlane_b32 s75, v208, 46
	v_readlane_b32 s76, v208, 47
	v_readlane_b32 s77, v208, 48
	v_readlane_b32 s78, v208, 49
	v_readlane_b32 s79, v208, 50
	v_readlane_b32 s61, v209, 4
	v_readlane_b32 s62, v209, 5
	v_readlane_b32 s63, v209, 6
	v_readlane_b32 s64, v209, 7
	v_readlane_b32 s65, v209, 8
	v_readlane_b32 s66, v209, 9
	s_mov_b32 s56, 0x10000
	s_mov_b32 s57, 0x20000
	s_mov_b32 s58, 0x30000
	s_movk_i32 s59, 0x70
	s_movk_i32 s49, 0x2200
	s_movk_i32 s53, 0x2000
	s_mov_b32 s52, 0xb000
	s_mov_b32 s67, 0x3a000
	s_branch .LBB0_680
.LBB0_679:
	s_add_u32 s36, s36, 1
	s_addc_u32 s37, s37, 0
	s_add_u32 s2, s2, 0x80
	s_addc_u32 s3, s3, 0
	v_readlane_b32 vcc_lo, v206, 41
	s_cmp_lg_u32 s2, vcc_lo
	s_cbranch_scc0 .LBB0_701

.LBB0_706:
	s_mov_b32 s4, 0xb000
	s_movk_i32 s1, 0x2000
	s_or_b64 exec, exec, s[2:3]
	v_readlane_b32 s0, v207, 0
	v_readlane_b32 s44, v210, 18
	v_readlane_b32 s56, v210, 30
	v_add_u32_e32 v4, s0, v2
	v_ashrrev_i32_e32 v5, 31, v4
	v_lshlrev_b64 v[4:5], 2, v[4:5]
	v_readlane_b32 s57, v210, 31
	v_readlane_b32 s80, v210, 34
	v_readlane_b32 s58, v210, 32
	v_readlane_b32 s59, v210, 33
	v_lshl_add_u64 v[6:7], s[56:57], 0, v[4:5]
	v_readlane_b32 s81, v210, 35
	v_readlane_b32 s2, v207, 3
	global_load_dword v0, v[6:7], off
	v_lshl_add_u64 v[6:7], s[58:59], 0, v[4:5]
	v_lshl_add_u64 v[4:5], s[80:81], 0, v[4:5]
	v_ashrrev_i32_e32 v3, 31, v2
	v_readlane_b32 s3, v207, 4
	global_load_dword v55, v[4:5], off
	s_mov_b32 s0, 0x8000
	v_lshl_add_u64 v[4:5], v[2:3], 2, s[2:3]
	global_load_dword v54, v[6:7], off
	v_lshlrev_b32_e32 v96, 2, v2
	global_load_dword v6, v96, s[2:3]
	global_load_dword v7, v96, s[2:3] offset:1024
	global_load_dword v8, v96, s[2:3] offset:2048
	global_load_dword v9, v96, s[2:3] offset:3072
	v_add_u32_e32 v96, 0x1000, v96
	global_load_dword v10, v96, s[2:3]
	global_load_dword v11, v96, s[2:3] offset:1024
	global_load_dword v12, v96, s[2:3] offset:2048
	global_load_dword v13, v96, s[2:3] offset:3072
	v_add_u32_e32 v96, 0x1000, v96
	global_load_dword v14, v96, s[2:3]
	global_load_dword v15, v96, s[2:3] offset:1024
	global_load_dword v16, v96, s[2:3] offset:2048
	global_load_dword v17, v96, s[2:3] offset:3072
	v_add_u32_e32 v96, 0x1000, v96
	global_load_dword v18, v96, s[2:3]
	global_load_dword v19, v96, s[2:3] offset:1024
	global_load_dword v20, v96, s[2:3] offset:2048
	global_load_dword v21, v96, s[2:3] offset:3072
	v_add_u32_e32 v96, 0x1000, v96
	global_load_dword v22, v96, s[2:3]
	global_load_dword v23, v96, s[2:3] offset:1024
	global_load_dword v24, v96, s[2:3] offset:2048
	global_load_dword v25, v96, s[2:3] offset:3072
	v_add_u32_e32 v96, 0x1000, v96
	global_load_dword v26, v96, s[2:3]
	global_load_dword v27, v96, s[2:3] offset:1024
	global_load_dword v28, v96, s[2:3] offset:2048
	global_load_dword v29, v96, s[2:3] offset:3072
	v_add_u32_e32 v96, 0x1000, v96
	global_load_dword v30, v96, s[2:3]
	global_load_dword v31, v96, s[2:3] offset:1024
	global_load_dword v32, v96, s[2:3] offset:2048
	global_load_dword v33, v96, s[2:3] offset:3072
	v_add_u32_e32 v96, 0x1000, v96
	global_load_dword v34, v96, s[2:3]
	global_load_dword v35, v96, s[2:3] offset:1024
	global_load_dword v36, v96, s[2:3] offset:2048
	global_load_dword v37, v96, s[2:3] offset:3072
	v_add_u32_e32 v96, 0x1000, v96
	global_load_dword v56, v96, s[2:3]
	global_load_dword v57, v96, s[2:3] offset:1024
	global_load_dword v58, v96, s[2:3] offset:2048
	global_load_dword v59, v96, s[2:3] offset:3072
	v_add_u32_e32 v96, 0x1000, v96
	global_load_dword v60, v96, s[2:3]
	global_load_dword v61, v96, s[2:3] offset:1024
	global_load_dword v62, v96, s[2:3] offset:2048
	global_load_dword v63, v96, s[2:3] offset:3072
	v_add_u32_e32 v96, 0x1000, v96
	global_load_dword v64, v96, s[2:3]
	global_load_dword v65, v96, s[2:3] offset:1024
	global_load_dword v66, v96, s[2:3] offset:2048
	global_load_dword v67, v96, s[2:3] offset:3072
	v_add_u32_e32 v96, 0x1000, v96
	global_load_dword v68, v96, s[2:3]
	global_load_dword v69, v96, s[2:3] offset:1024
	global_load_dword v70, v96, s[2:3] offset:2048
	global_load_dword v71, v96, s[2:3] offset:3072
	v_add_u32_e32 v96, 0x1000, v96
	global_load_dword v72, v96, s[2:3]
	global_load_dword v73, v96, s[2:3] offset:1024
	global_load_dword v74, v96, s[2:3] offset:2048
	global_load_dword v75, v96, s[2:3] offset:3072
	v_add_u32_e32 v96, 0x1000, v96
	global_load_dword v76, v96, s[2:3]
	global_load_dword v77, v96, s[2:3] offset:1024
	global_load_dword v78, v96, s[2:3] offset:2048
	global_load_dword v79, v96, s[2:3] offset:3072
	v_add_u32_e32 v96, 0x1000, v96
	global_load_dword v80, v96, s[2:3]
	global_load_dword v81, v96, s[2:3] offset:1024
	global_load_dword v82, v96, s[2:3] offset:2048
	global_load_dword v83, v96, s[2:3] offset:3072
	v_add_u32_e32 v96, 0x1000, v96
	global_load_dword v84, v96, s[2:3]
	global_load_dword v85, v96, s[2:3] offset:1024
	global_load_dword v86, v96, s[2:3] offset:2048
	global_load_dword v87, v96, s[2:3] offset:3072
	s_waitcnt lgkmcnt(0)
	s_barrier
	s_movk_i32 s3, 0x4000
	s_movk_i32 s0, 0x1000
	s_nop 0
	s_mov_b32 s0, 0x9000
	s_nop 0
	s_mov_b32 s0, 0xa000
	s_nop 0
	s_movk_i32 s0, 0x3000
	s_nop 0
	s_mov_b32 s0, 0xc000
	s_nop 0
	s_nop 0
	s_nop 0
	s_movk_i32 s0, 0x5000
	s_nop 0
	s_mov_b32 s0, 0xd000
	s_nop 0
	s_movk_i32 s0, 0x6000
	s_nop 0
	s_mov_b32 s0, 0xe000
	s_nop 0
	s_movk_i32 s0, 0x7000
	s_nop 0
	s_mov_b32 s0, 0xf000
	s_nop 0
	s_nop 0
	s_nop 0
	s_nop 0
	s_nop 0
	s_nop 0
	s_nop 0
	v_readlane_b32 s0, v207, 2
	v_readlane_b32 s48, v210, 22
	v_readlane_b32 s49, v210, 23
	v_add_u32_e32 v4, s0, v2
	v_ashrrev_i32_e32 v5, 31, v4
	v_lshl_add_u64 v[100:101], v[4:5], 2, s[48:49]
	global_load_dword v88, v[100:101], off
	global_load_dword v89, v[100:101], off offset:1024
	s_mov_b32 s2, 0
	s_mov_b32 s0, s97
	v_readlane_b32 s45, v210, 19
	v_readlane_b32 s46, v210, 20
	v_readlane_b32 s47, v210, 21
	v_readlane_b32 s50, v210, 24
	v_readlane_b32 s51, v210, 25
	v_readlane_b32 s52, v210, 26
	v_readlane_b32 s53, v210, 27
	v_readlane_b32 s54, v210, 28
	v_readlane_b32 s55, v210, 29
	v_readlane_b32 s82, v210, 36
	v_readlane_b32 s83, v210, 37
	v_readlane_b32 s84, v210, 38
	v_readlane_b32 s85, v210, 39
	v_readlane_b32 s86, v210, 40
	v_readlane_b32 s87, v210, 41
	v_readlane_b32 s88, v210, 42
	v_readlane_b32 s89, v210, 43
	v_readlane_b32 s90, v210, 44
	v_readlane_b32 s91, v210, 45
	v_readlane_b32 s92, v210, 46
	v_readlane_b32 s93, v210, 47
	v_readlane_b32 s94, v210, 48
	v_readlane_b32 s95, v210, 49
	s_waitcnt vmcnt(0)
	v_mov_b32_e32 v94, 0
	ds_read_b128 v[136:139], v94 offset:0
	ds_read_b128 v[140:143], v94 offset:128
	ds_read_b128 v[144:147], v94 offset:16
	ds_read_b128 v[148:151], v94 offset:144
	ds_read_b128 v[152:155], v94 offset:32
	ds_read_b128 v[156:159], v94 offset:160
	ds_read_b128 v[160:163], v94 offset:48
	ds_read_b128 v[164:167], v94 offset:176
	ds_read_b128 v[184:187], v94 offset:64
	ds_read_b128 v[188:191], v94 offset:192
	ds_read_b128 v[192:195], v94 offset:80
	ds_read_b128 v[196:199], v94 offset:208
	ds_read_b128 v[200:203], v94 offset:96
	ds_read_b128 v[212:215], v94 offset:224
	ds_read_b128 v[216:219], v94 offset:112
	ds_read_b128 v[220:223], v94 offset:240
	s_lshl_b32 s4, s97, 10
	v_lshlrev_b32_e32 v95, 2, v2
	v_add_u32_e32 v95, s4, v95
.LBB0_707:
	v_mov_b32_e32 v94, s2
	s_waitcnt lgkmcnt(15)
	v_pk_mul_f32 v[90:91], v[136:137], v[6:7]
	v_pk_fma_f32 v[90:91], v[138:139], v[8:9], v[90:91]
	ds_read_b128 v[136:139], v94 offset:512
	s_waitcnt lgkmcnt(15)
	v_pk_mul_f32 v[92:93], v[140:141], v[56:57]
	v_pk_fma_f32 v[92:93], v[142:143], v[58:59], v[92:93]
	ds_read_b128 v[140:143], v94 offset:640
	s_waitcnt lgkmcnt(15)
	v_pk_fma_f32 v[90:91], v[144:145], v[10:11], v[90:91]
	v_pk_fma_f32 v[90:91], v[146:147], v[12:13], v[90:91]
	ds_read_b128 v[144:147], v94 offset:528
	s_waitcnt lgkmcnt(15)
	v_pk_fma_f32 v[92:93], v[148:149], v[60:61], v[92:93]
	v_pk_fma_f32 v[92:93], v[150:151], v[62:63], v[92:93]
	ds_read_b128 v[148:151], v94 offset:656
	s_waitcnt lgkmcnt(15)
	v_pk_fma_f32 v[90:91], v[152:153], v[14:15], v[90:91]
	v_pk_fma_f32 v[90:91], v[154:155], v[16:17], v[90:91]
	ds_read_b128 v[152:155], v94 offset:544
	s_waitcnt lgkmcnt(15)
	v_pk_fma_f32 v[92:93], v[156:157], v[64:65], v[92:93]
	v_pk_fma_f32 v[92:93], v[158:159], v[66:67], v[92:93]
	ds_read_b128 v[156:159], v94 offset:672
	s_waitcnt lgkmcnt(15)
	v_pk_fma_f32 v[90:91], v[160:161], v[18:19], v[90:91]
	v_pk_fma_f32 v[90:91], v[162:163], v[20:21], v[90:91]
	ds_read_b128 v[160:163], v94 offset:560
	s_waitcnt lgkmcnt(15)
	v_pk_fma_f32 v[92:93], v[164:165], v[68:69], v[92:93]
	v_pk_fma_f32 v[92:93], v[166:167], v[70:71], v[92:93]
	ds_read_b128 v[164:167], v94 offset:688
	s_waitcnt lgkmcnt(15)
	v_pk_fma_f32 v[90:91], v[184:185], v[22:23], v[90:91]
	v_pk_fma_f32 v[90:91], v[186:187], v[24:25], v[90:91]
	ds_read_b128 v[184:187], v94 offset:576
	s_waitcnt lgkmcnt(15)
	v_pk_fma_f32 v[92:93], v[188:189], v[72:73], v[92:93]
	v_pk_fma_f32 v[92:93], v[190:191], v[74:75], v[92:93]
	ds_read_b128 v[188:191], v94 offset:704
	s_waitcnt lgkmcnt(15)
	v_pk_fma_f32 v[90:91], v[192:193], v[26:27], v[90:91]
	v_pk_fma_f32 v[90:91], v[194:195], v[28:29], v[90:91]
	ds_read_b128 v[192:195], v94 offset:592
	s_waitcnt lgkmcnt(15)
	v_pk_fma_f32 v[92:93], v[196:197], v[76:77], v[92:93]
	v_pk_fma_f32 v[92:93], v[198:199], v[78:79], v[92:93]
	ds_read_b128 v[196:199], v94 offset:720
	s_waitcnt lgkmcnt(15)
	v_pk_fma_f32 v[90:91], v[200:201], v[30:31], v[90:91]
	v_pk_fma_f32 v[90:91], v[202:203], v[32:33], v[90:91]
	ds_read_b128 v[200:203], v94 offset:608
	s_waitcnt lgkmcnt(15)
	v_pk_fma_f32 v[92:93], v[212:213], v[80:81], v[92:93]
	v_pk_fma_f32 v[92:93], v[214:215], v[82:83], v[92:93]
	ds_read_b128 v[212:215], v94 offset:736
	s_waitcnt lgkmcnt(15)
	v_pk_fma_f32 v[90:91], v[216:217], v[34:35], v[90:91]
	v_pk_fma_f32 v[90:91], v[218:219], v[36:37], v[90:91]
	ds_read_b128 v[216:219], v94 offset:624
	s_waitcnt lgkmcnt(15)
	v_pk_fma_f32 v[92:93], v[220:221], v[84:85], v[92:93]
	v_pk_fma_f32 v[92:93], v[222:223], v[86:87], v[92:93]
	ds_read_b128 v[220:223], v94 offset:752
	s_addk_i32 s2, 0x200
	v_add_f32_e32 v98, v90, v88
	v_add_f32_e32 v99, v92, v89
	v_add_f32_e32 v98, v98, v91
	v_add_f32_e32 v99, v99, v93
	v_mul_f32_e32 v98, 0xbfb8aa3b, v98
	v_mul_f32_e32 v99, 0xbfb8aa3b, v99
	v_exp_f32_e32 v98, v98
	v_exp_f32_e32 v99, v99
	s_nop 0
	v_add_f32_e32 v98, 1.0, v98
	v_add_f32_e32 v99, 1.0, v99
	v_rcp_f32_e32 v98, v98
	v_rcp_f32_e32 v99, v99
	s_nop 0
	v_mul_f32_e32 v98, 0xbf60028a, v98
	v_mul_f32_e32 v99, 0xbf60028a, v99
	v_exp_f32_e32 v98, v98
	v_exp_f32_e32 v99, v99
	s_cmpk_eq_i32 s2, 0x4400
	s_nop 0
	global_store_dword v95, v98, s[14:15]
	global_store_dword v95, v99, s[16:17]
	v_add_u32_e32 v95, 0x400, v95
	s_cbranch_scc0 .LBB0_707
	s_waitcnt lgkmcnt(0)
	v_lshlrev_b64 v[6:7], 2, v[2:3]
	v_lshl_add_u64 v[66:67], s[68:69], 0, v[6:7]
	v_mov_b32_e32 v96, v6
	global_load_dword v8, v96, s[68:69]
	global_load_dword v9, v96, s[68:69] offset:1024
	global_load_dword v10, v96, s[68:69] offset:2048
	global_load_dword v11, v96, s[68:69] offset:3072
	v_add_u32_e32 v96, 0x1000, v96
	global_load_dword v12, v96, s[68:69]
	global_load_dword v13, v96, s[68:69] offset:1024
	global_load_dword v14, v96, s[68:69] offset:2048
	global_load_dword v15, v96, s[68:69] offset:3072
	v_add_u32_e32 v96, 0x1000, v96
	global_load_dword v16, v96, s[68:69]
	global_load_dword v17, v96, s[68:69] offset:1024
	global_load_dword v18, v96, s[68:69] offset:2048
	global_load_dword v19, v96, s[68:69] offset:3072
	v_add_u32_e32 v96, 0x1000, v96
	global_load_dword v20, v96, s[68:69]
	global_load_dword v21, v96, s[68:69] offset:1024
	global_load_dword v22, v96, s[68:69] offset:2048
	global_load_dword v23, v96, s[68:69] offset:3072
	v_add_u32_e32 v96, 0x1000, v96
	global_load_dword v24, v96, s[68:69]
	global_load_dword v25, v96, s[68:69] offset:1024
	global_load_dword v26, v96, s[68:69] offset:2048
	global_load_dword v27, v96, s[68:69] offset:3072
	v_add_u32_e32 v96, 0x1000, v96
	global_load_dword v28, v96, s[68:69]
	global_load_dword v29, v96, s[68:69] offset:1024
	global_load_dword v30, v96, s[68:69] offset:2048
	global_load_dword v31, v96, s[68:69] offset:3072
	v_add_u32_e32 v96, 0x1000, v96
	global_load_dword v32, v96, s[68:69]
	global_load_dword v33, v96, s[68:69] offset:1024
	global_load_dword v34, v96, s[68:69] offset:2048
	global_load_dword v35, v96, s[68:69] offset:3072
	v_add_u32_e32 v96, 0x1000, v96
	global_load_dword v36, v96, s[68:69]
	global_load_dword v37, v96, s[68:69] offset:1024
	global_load_dword v38, v96, s[68:69] offset:2048
	global_load_dword v39, v96, s[68:69] offset:3072
	v_add_u32_e32 v96, 0x1000, v96
	global_load_dword v56, v96, s[68:69]
	global_load_dword v57, v96, s[68:69] offset:1024
	global_load_dword v58, v96, s[68:69] offset:2048
	global_load_dword v59, v96, s[68:69] offset:3072
	v_add_u32_e32 v96, 0x1000, v96
	global_load_dword v60, v96, s[68:69]
	global_load_dword v61, v96, s[68:69] offset:1024
	global_load_dword v62, v96, s[68:69] offset:2048
	global_load_dword v63, v96, s[68:69] offset:3072
	v_add_u32_e32 v96, 0x1000, v96
	global_load_dword v64, v96, s[68:69]
	global_load_dword v65, v96, s[68:69] offset:1024
	global_load_dword v66, v96, s[68:69] offset:2048
	global_load_dword v67, v96, s[68:69] offset:3072
	v_add_u32_e32 v96, 0x1000, v96
	global_load_dword v68, v96, s[68:69]
	global_load_dword v69, v96, s[68:69] offset:1024
	global_load_dword v70, v96, s[68:69] offset:2048
	global_load_dword v71, v96, s[68:69] offset:3072
	v_add_u32_e32 v96, 0x1000, v96
	global_load_dword v72, v96, s[68:69]
	global_load_dword v73, v96, s[68:69] offset:1024
	global_load_dword v74, v96, s[68:69] offset:2048
	global_load_dword v75, v96, s[68:69] offset:3072
	v_add_u32_e32 v96, 0x1000, v96
	global_load_dword v76, v96, s[68:69]
	global_load_dword v77, v96, s[68:69] offset:1024
	global_load_dword v78, v96, s[68:69] offset:2048
	global_load_dword v79, v96, s[68:69] offset:3072
	v_add_u32_e32 v96, 0x1000, v96
	global_load_dword v80, v96, s[68:69]
	global_load_dword v81, v96, s[68:69] offset:1024
	global_load_dword v82, v96, s[68:69] offset:2048
	global_load_dword v83, v96, s[68:69] offset:3072
	v_add_u32_e32 v96, 0x1000, v96
	global_load_dword v84, v96, s[68:69]
	global_load_dword v85, v96, s[68:69] offset:1024
	global_load_dword v86, v96, s[68:69] offset:2048
	global_load_dword v87, v96, s[68:69] offset:3072
	s_mov_b32 s0, 0xc000
	v_readlane_b32 s44, v210, 18
	s_nop 0
	s_nop 0
	s_nop 0
	v_readlane_b32 s52, v210, 26
	s_nop 0
	s_nop 0
	s_nop 0
	v_readlane_b32 s53, v210, 27
	s_nop 0
	s_nop 0
	s_nop 0
	v_lshl_add_u64 v[4:5], v[4:5], 2, s[52:53]
	s_nop 0
	s_nop 0
	s_nop 0
	s_movk_i32 s0, 0x5000
	s_nop 0
	s_mov_b32 s0, 0xd000
	s_nop 0
	s_movk_i32 s0, 0x6000
	s_nop 0
	s_mov_b32 s0, 0xe000
	s_nop 0
	s_movk_i32 s0, 0x7000
	s_nop 0
	s_mov_b32 s0, 0xf000
	s_nop 0
	s_nop 0
	s_nop 0
	s_nop 0
	s_nop 0
	s_nop 0
	s_nop 0
	s_nop 0
	s_nop 0
	s_nop 0
	s_nop 0
	s_nop 0
	global_load_dword v88, v[4:5], off
	global_load_dword v89, v[4:5], off offset:1024
	v_and_b32_e32 v5, 63, v2
	v_ashrrev_i32_e32 v4, 6, v2
	v_readlane_b32 s56, v210, 30
	v_readlane_b32 s57, v210, 31
	v_readlane_b32 s58, v210, 32
	v_readlane_b32 s59, v210, 33
	v_cmp_eq_u32_e32 vcc, 0, v5
	v_ashrrev_i32_e32 v5, 31, v4
	v_readlane_b32 s80, v208, 27
	s_movk_i32 s61, 0x4000
	s_mov_b32 s6, 0
	v_lshl_add_u64 v[4:5], v[4:5], 2, s[24:25]
	v_lshl_add_u64 v[6:7], s[12:13], 0, v[6:7]
	s_movk_i32 s7, 0x100
	v_readlane_b32 s81, v208, 28
	v_readlane_b32 s82, v208, 29
	v_readlane_b32 s83, v208, 30
	v_readlane_b32 s84, v208, 31
	v_readlane_b32 s85, v208, 32
	v_readlane_b32 s86, v208, 33
	v_readlane_b32 s87, v208, 34
	v_readlane_b32 s88, v208, 35
	v_readlane_b32 s89, v208, 36
	v_readlane_b32 s90, v208, 37
	v_readlane_b32 s91, v208, 38
	v_readlane_b32 s92, v208, 39
	v_readlane_b32 s93, v208, 40
	v_readlane_b32 s94, v208, 41
	v_readlane_b32 s95, v208, 42
	s_mov_b32 s56, 0x10000
	s_mov_b32 s57, 0x20000
	s_mov_b32 s58, 0x30000
	s_movk_i32 s59, 0x70
	v_readlane_b32 s45, v210, 19
	v_readlane_b32 s46, v210, 20
	v_readlane_b32 s47, v210, 21
	v_readlane_b32 s48, v210, 22
	v_readlane_b32 s49, v210, 23
	v_readlane_b32 s50, v210, 24
	v_readlane_b32 s51, v210, 25
	v_readlane_b32 s54, v210, 28
	v_readlane_b32 s55, v210, 29
	s_waitcnt vmcnt(0) lgkmcnt(0)
	v_mov_b32_e32 v94, s7
	ds_read_b128 v[136:139], v94 offset:0
	ds_read_b128 v[140:143], v94 offset:128
	ds_read_b128 v[144:147], v94 offset:16
	ds_read_b128 v[148:151], v94 offset:144
	ds_read_b128 v[152:155], v94 offset:32
	ds_read_b128 v[156:159], v94 offset:160
	ds_read_b128 v[160:163], v94 offset:48
	ds_read_b128 v[164:167], v94 offset:176
	ds_read_b128 v[184:187], v94 offset:64
	ds_read_b128 v[188:191], v94 offset:192
	ds_read_b128 v[192:195], v94 offset:80
	ds_read_b128 v[196:199], v94 offset:208
	ds_read_b128 v[200:203], v94 offset:96
	ds_read_b128 v[212:215], v94 offset:224
	ds_read_b128 v[216:219], v94 offset:112
	ds_read_b128 v[220:223], v94 offset:240
	s_lshl_b32 s4, s97, 10
	v_lshlrev_b32_e32 v95, 2, v2
	v_add_u32_e32 v95, s4, v95
	s_mov_b32 s1, 0
	v_mad_i64_i32 v[44:45], s[2:3], s97, v178, v[6:7]
	global_load_dword v42, v[44:45], off
	global_load_dword v43, v[44:45], off offset:1024
.LBB0_710:
	v_mov_b32_e32 v94, s7
	s_add_i32 s0, s97, s6
	s_waitcnt vmcnt(0)
	v_mul_f32_e32 v97, v0, v43
	v_mul_f32_e32 v102, v97, v97
	s_waitcnt lgkmcnt(15)
	v_pk_mul_f32 v[90:91], v[136:137], v[8:9]
	v_pk_fma_f32 v[90:91], v[138:139], v[10:11], v[90:91]
	ds_read_b128 v[136:139], v94 offset:512
	v_add_f32_dpp v102, v102, v102 quad_perm:[1,0,3,2] row_mask:0xf bank_mask:0xf bound_ctrl:1
	s_waitcnt lgkmcnt(15)
	v_pk_mul_f32 v[92:93], v[140:141], v[56:57]
	v_pk_fma_f32 v[92:93], v[142:143], v[58:59], v[92:93]
	ds_read_b128 v[140:143], v94 offset:640
	v_add_f32_dpp v102, v102, v102 quad_perm:[2,3,0,1] row_mask:0xf bank_mask:0xf bound_ctrl:1
	s_waitcnt lgkmcnt(15)
	v_pk_fma_f32 v[90:91], v[144:145], v[12:13], v[90:91]
	v_pk_fma_f32 v[90:91], v[146:147], v[14:15], v[90:91]
	ds_read_b128 v[144:147], v94 offset:528
	v_add_f32_dpp v102, v102, v102 row_half_mirror row_mask:0xf bank_mask:0xf bound_ctrl:1
	s_waitcnt lgkmcnt(15)
	v_pk_fma_f32 v[92:93], v[148:149], v[60:61], v[92:93]
	v_pk_fma_f32 v[92:93], v[150:151], v[62:63], v[92:93]
	ds_read_b128 v[148:151], v94 offset:656
	v_add_f32_dpp v102, v102, v102 row_mirror row_mask:0xf bank_mask:0xf bound_ctrl:1
	s_waitcnt lgkmcnt(15)
	v_pk_fma_f32 v[90:91], v[152:153], v[16:17], v[90:91]
	v_pk_fma_f32 v[90:91], v[154:155], v[18:19], v[90:91]
	ds_read_b128 v[152:155], v94 offset:544
	v_add_f32_dpp v102, v102, v102 row_bcast:15 row_mask:0xa bank_mask:0xf
	s_waitcnt lgkmcnt(15)
	v_pk_fma_f32 v[92:93], v[156:157], v[64:65], v[92:93]
	v_pk_fma_f32 v[92:93], v[158:159], v[66:67], v[92:93]
	ds_read_b128 v[156:159], v94 offset:672
	v_add_f32_dpp v102, v102, v102 row_bcast:31 row_mask:0xc bank_mask:0xf
	s_waitcnt lgkmcnt(15)
	v_pk_fma_f32 v[90:91], v[160:161], v[20:21], v[90:91]
	v_pk_fma_f32 v[90:91], v[162:163], v[22:23], v[90:91]
	ds_read_b128 v[160:163], v94 offset:560
	s_waitcnt lgkmcnt(15)
	v_pk_fma_f32 v[92:93], v[164:165], v[68:69], v[92:93]
	v_pk_fma_f32 v[92:93], v[166:167], v[70:71], v[92:93]
	ds_read_b128 v[164:167], v94 offset:688
	s_waitcnt lgkmcnt(15)
	v_pk_fma_f32 v[90:91], v[184:185], v[24:25], v[90:91]
	v_pk_fma_f32 v[90:91], v[186:187], v[26:27], v[90:91]
	ds_read_b128 v[184:187], v94 offset:576
	v_readlane_b32 s8, v102, 63
	s_waitcnt lgkmcnt(15)
	v_pk_fma_f32 v[92:93], v[188:189], v[72:73], v[92:93]
	v_pk_fma_f32 v[92:93], v[190:191], v[74:75], v[92:93]
	ds_read_b128 v[188:191], v94 offset:704
	s_waitcnt lgkmcnt(15)
	v_pk_fma_f32 v[90:91], v[192:193], v[28:29], v[90:91]
	v_pk_fma_f32 v[90:91], v[194:195], v[30:31], v[90:91]
	ds_read_b128 v[192:195], v94 offset:592
	s_waitcnt lgkmcnt(15)
	v_pk_fma_f32 v[92:93], v[196:197], v[76:77], v[92:93]
	v_pk_fma_f32 v[92:93], v[198:199], v[78:79], v[92:93]
	ds_read_b128 v[196:199], v94 offset:720
	s_waitcnt lgkmcnt(15)
	v_pk_fma_f32 v[90:91], v[200:201], v[32:33], v[90:91]
	v_pk_fma_f32 v[90:91], v[202:203], v[34:35], v[90:91]
	ds_read_b128 v[200:203], v94 offset:608
	s_waitcnt lgkmcnt(15)
	v_pk_fma_f32 v[92:93], v[212:213], v[80:81], v[92:93]
	v_pk_fma_f32 v[92:93], v[214:215], v[82:83], v[92:93]
	ds_read_b128 v[212:215], v94 offset:736
	s_waitcnt lgkmcnt(15)
	v_pk_fma_f32 v[90:91], v[216:217], v[36:37], v[90:91]
	v_pk_fma_f32 v[90:91], v[218:219], v[38:39], v[90:91]
	ds_read_b128 v[216:219], v94 offset:624
	s_waitcnt lgkmcnt(15)
	v_pk_fma_f32 v[92:93], v[220:221], v[84:85], v[92:93]
	v_pk_fma_f32 v[92:93], v[222:223], v[86:87], v[92:93]
	ds_read_b128 v[220:223], v94 offset:752
	v_add_f32_e32 v98, v90, v88
	v_add_f32_e32 v99, v92, v89
	v_add_f32_e32 v98, v98, v91
	v_add_f32_e32 v99, v99, v93
	v_mul_f32_e32 v98, 0xbfb8aa3b, v98
	v_mul_f32_e32 v99, 0xbfb8aa3b, v99
	v_exp_f32_e32 v98, v98
	v_exp_f32_e32 v99, v99
	v_mov_b32_e32 v103, s8
	v_add_f32_e32 v98, 1.0, v98
	v_add_f32_e32 v99, 1.0, v99
	v_rcp_f32_e32 v98, v98
	v_rcp_f32_e32 v99, v99
	v_max_f32_e32 v103, 0x179abe15, v103
	v_rsq_f32_e32 v103, v103
	v_add_f32_e32 v112, -1.0, v98
	v_add_f32_e32 v113, -1.0, v99
	v_fma_f32 v112, v54, v112, 1.0
	v_fma_f32 v113, v54, v113, 1.0
	v_mul_f32_e32 v112, v43, v112
	v_fmac_f32_e32 v112, v43, v113
	v_mul_f32_e32 v97, v97, v103
	v_mul_f32_e32 v112, v42, v112
	v_mul_f32_e32 v114, v55, v112
	global_store_dword v95, v98, s[18:19]
	global_store_dword v95, v99, s[20:21]
	v_add_f32_dpp v114, v114, v114 quad_perm:[1,0,3,2] row_mask:0xf bank_mask:0xf bound_ctrl:1
	global_store_dword v95, v97, s[22:23]
	s_add_i32 s8, s0, 1
	v_add_f32_dpp v114, v114, v114 quad_perm:[2,3,0,1] row_mask:0xf bank_mask:0xf bound_ctrl:1
	s_cmp_eq_u32 s6, 33
	s_cbranch_scc1 .Lrw2_noload
	v_mad_i64_i32 v[44:45], s[2:3], s8, v178, v[6:7]
	global_load_dword v42, v[44:45], off
	global_load_dword v43, v[44:45], off offset:1024
.Lrw2_noload:
	s_nop 1
	v_add_f32_dpp v114, v114, v114 row_half_mirror row_mask:0xf bank_mask:0xf bound_ctrl:1
	v_add_u32_e32 v95, 0x400, v95
	s_addk_i32 s7, 0x200
	v_add_f32_dpp v114, v114, v114 row_mirror row_mask:0xf bank_mask:0xf bound_ctrl:1
	s_nop 1
	v_add_f32_dpp v114, v114, v114 row_bcast:15 row_mask:0xa bank_mask:0xf
	s_nop 1
	v_add_f32_dpp v114, v114, v114 row_bcast:31 row_mask:0xc bank_mask:0xf
	s_nop 1
	v_readlane_b32 s9, v114, 63
	s_and_saveexec_b64 s[4:5], vcc
	v_mov_b32_e32 v103, s9
	v_lshl_add_u64 v[46:47], s[0:1], 4, v[4:5]
	global_store_dword v[46:47], v103, off
	s_or_b64 exec, exec, s[4:5]
	s_add_i32 s6, s6, 1
	s_cmp_lg_u32 s6, 34
	s_cbranch_scc1 .LBB0_710
	s_waitcnt lgkmcnt(0)
	s_branch .LBB0_671
